# adaLN matvec: four inner iterations fused, 32 row loads in flight per wave instead of 8
# baseline (speedup 1.0000x reference)
.LBB0_11:
	v_lshl_add_u64 v[16:17], v[6:7], 0, s[6:7]
	v_add_co_u32_e64 v18, s[0:1], s2, v16
	global_load_dword v56, v[16:17], off
	s_nop 0
	v_addc_co_u32_e64 v19, s[0:1], 0, v17, s[0:1]
	v_add_co_u32_e64 v20, s[0:1], s8, v16
	s_add_u32 s6, s6, 0x30000
	s_nop 0
	v_addc_co_u32_e64 v21, s[0:1], 0, v17, s[0:1]
	v_add_co_u32_e64 v22, s[0:1], s9, v16
	s_addc_u32 s7, s7, 0
	s_nop 0
	v_addc_co_u32_e64 v23, s[0:1], 0, v17, s[0:1]
	v_add_co_u32_e64 v24, s[0:1], s10, v16
	s_nop 0
	s_nop 0
	v_addc_co_u32_e64 v25, s[0:1], 0, v17, s[0:1]
	v_add_co_u32_e64 v26, s[0:1], s11, v16
	s_nop 1
	v_addc_co_u32_e64 v27, s[0:1], 0, v17, s[0:1]
	v_add_co_u32_e64 v28, s[0:1], s12, v16
	s_nop 1
	v_addc_co_u32_e64 v29, s[0:1], 0, v17, s[0:1]
	v_add_co_u32_e64 v16, s[0:1], s13, v16
	s_nop 1
	v_addc_co_u32_e64 v17, s[0:1], 0, v17, s[0:1]
	global_load_dword v58, v[18:19], off
	global_load_dword v60, v[20:21], off
	global_load_dword v62, v[22:23], off
	global_load_dword v64, v[24:25], off
	global_load_dword v66, v[26:27], off
	global_load_dword v68, v[28:29], off
	global_load_dword v70, v[16:17], off
	v_lshl_add_u64 v[16:17], v[6:7], 0, s[6:7]
	v_add_co_u32_e64 v18, s[0:1], s2, v16
	global_load_dword v76, v[16:17], off
	s_nop 0
	v_addc_co_u32_e64 v19, s[0:1], 0, v17, s[0:1]
	v_add_co_u32_e64 v20, s[0:1], s8, v16
	s_add_u32 s6, s6, 0x30000
	s_nop 0
	v_addc_co_u32_e64 v21, s[0:1], 0, v17, s[0:1]
	v_add_co_u32_e64 v22, s[0:1], s9, v16
	s_addc_u32 s7, s7, 0
	s_nop 0
	v_addc_co_u32_e64 v23, s[0:1], 0, v17, s[0:1]
	v_add_co_u32_e64 v24, s[0:1], s10, v16
	s_nop 0
	s_nop 0
	v_addc_co_u32_e64 v25, s[0:1], 0, v17, s[0:1]
	v_add_co_u32_e64 v26, s[0:1], s11, v16
	s_nop 1
	v_addc_co_u32_e64 v27, s[0:1], 0, v17, s[0:1]
	v_add_co_u32_e64 v28, s[0:1], s12, v16
	s_nop 1
	v_addc_co_u32_e64 v29, s[0:1], 0, v17, s[0:1]
	v_add_co_u32_e64 v16, s[0:1], s13, v16
	s_nop 1
	v_addc_co_u32_e64 v17, s[0:1], 0, v17, s[0:1]
	global_load_dword v78, v[18:19], off
	global_load_dword v80, v[20:21], off
	global_load_dword v82, v[22:23], off
	global_load_dword v84, v[24:25], off
	global_load_dword v86, v[26:27], off
	global_load_dword v88, v[28:29], off
	global_load_dword v90, v[16:17], off
	v_lshl_add_u64 v[16:17], v[6:7], 0, s[6:7]
	v_add_co_u32_e64 v18, s[0:1], s2, v16
	global_load_dword v92, v[16:17], off
	s_nop 0
	v_addc_co_u32_e64 v19, s[0:1], 0, v17, s[0:1]
	v_add_co_u32_e64 v20, s[0:1], s8, v16
	s_add_u32 s6, s6, 0x30000
	s_nop 0
	v_addc_co_u32_e64 v21, s[0:1], 0, v17, s[0:1]
	v_add_co_u32_e64 v22, s[0:1], s9, v16
	s_addc_u32 s7, s7, 0
	s_nop 0
	v_addc_co_u32_e64 v23, s[0:1], 0, v17, s[0:1]
	v_add_co_u32_e64 v24, s[0:1], s10, v16
	s_nop 0
	s_nop 0
	v_addc_co_u32_e64 v25, s[0:1], 0, v17, s[0:1]
	v_add_co_u32_e64 v26, s[0:1], s11, v16
	s_nop 1
	v_addc_co_u32_e64 v27, s[0:1], 0, v17, s[0:1]
	v_add_co_u32_e64 v28, s[0:1], s12, v16
	s_nop 1
	v_addc_co_u32_e64 v29, s[0:1], 0, v17, s[0:1]
	v_add_co_u32_e64 v16, s[0:1], s13, v16
	s_nop 1
	v_addc_co_u32_e64 v17, s[0:1], 0, v17, s[0:1]
	global_load_dword v94, v[18:19], off
	global_load_dword v96, v[20:21], off
	global_load_dword v98, v[22:23], off
	global_load_dword v100, v[24:25], off
	global_load_dword v102, v[26:27], off
	global_load_dword v104, v[28:29], off
	global_load_dword v106, v[16:17], off
	v_lshl_add_u64 v[16:17], v[6:7], 0, s[6:7]
	v_add_co_u32_e64 v18, s[0:1], s2, v16
	global_load_dword v108, v[16:17], off
	s_nop 0
	v_addc_co_u32_e64 v19, s[0:1], 0, v17, s[0:1]
	v_add_co_u32_e64 v20, s[0:1], s8, v16
	s_add_u32 s6, s6, 0x30000
	s_nop 0
	v_addc_co_u32_e64 v21, s[0:1], 0, v17, s[0:1]
	v_add_co_u32_e64 v22, s[0:1], s9, v16
	s_addc_u32 s7, s7, 0
	s_nop 0
	v_addc_co_u32_e64 v23, s[0:1], 0, v17, s[0:1]
	v_add_co_u32_e64 v24, s[0:1], s10, v16
	s_nop 0
	s_nop 0
	v_addc_co_u32_e64 v25, s[0:1], 0, v17, s[0:1]
	v_add_co_u32_e64 v26, s[0:1], s11, v16
	s_nop 1
	v_addc_co_u32_e64 v27, s[0:1], 0, v17, s[0:1]
	v_add_co_u32_e64 v28, s[0:1], s12, v16
	s_nop 1
	v_addc_co_u32_e64 v29, s[0:1], 0, v17, s[0:1]
	v_add_co_u32_e64 v16, s[0:1], s13, v16
	s_nop 1
	v_addc_co_u32_e64 v17, s[0:1], 0, v17, s[0:1]
	global_load_dword v110, v[18:19], off
	global_load_dword v112, v[20:21], off
	global_load_dword v114, v[22:23], off
	global_load_dword v116, v[24:25], off
	global_load_dword v118, v[26:27], off
	global_load_dword v120, v[28:29], off
	global_load_dword v122, v[16:17], off
	ds_read_b128 v[16:19], v14
	ds_read_b128 v[20:23], v14 offset:16
	ds_read_b128 v[24:27], v14 offset:4096
	ds_read_b128 v[28:31], v14 offset:4112
	ds_read_b128 v[32:35], v14 offset:8192
	ds_read_b128 v[36:39], v14 offset:8208
	ds_read_b128 v[40:43], v14 offset:12288
	ds_read_b128 v[44:47], v14 offset:12304
	ds_read_b128 v[48:51], v14 offset:16384
	ds_read_b128 v[52:55], v14 offset:16400
	s_waitcnt lgkmcnt(5)
	v_mov_b32_e32 v72, v32
	v_mov_b32_e32 v73, v24
	s_waitcnt lgkmcnt(3)
	v_mov_b32_e32 v75, v40
	s_waitcnt lgkmcnt(1)
	v_mov_b32_e32 v74, v48
	v_mov_b32_e32 v24, v33
	v_mov_b32_e32 v40, v49
	v_mov_b32_e32 v32, v34
	v_mov_b32_e32 v33, v26
	v_mov_b32_e32 v48, v50
	v_mov_b32_e32 v49, v42
	v_mov_b32_e32 v26, v35
	v_mov_b32_e32 v42, v51
	v_mov_b32_e32 v34, v36
	v_mov_b32_e32 v35, v28
	s_waitcnt lgkmcnt(0)
	v_mov_b32_e32 v50, v52
	v_mov_b32_e32 v51, v44
	v_mov_b32_e32 v28, v37
	v_mov_b32_e32 v44, v53
	v_mov_b32_e32 v36, v38
	v_mov_b32_e32 v37, v30
	v_mov_b32_e32 v52, v54
	v_mov_b32_e32 v53, v46
	v_mov_b32_e32 v30, v39
	v_mov_b32_e32 v46, v55
	v_add_u32_e32 v14, 32, v14
	s_waitcnt vmcnt(31)
	v_fmac_f32_e32 v15, v56, v16
	v_pk_fma_f32 v[10:11], v[56:57], v[72:73], v[10:11] op_sel_hi:[0,1,1]
	v_pk_fma_f32 v[8:9], v[56:57], v[74:75], v[8:9] op_sel_hi:[0,1,1]
	s_waitcnt vmcnt(30)
	v_fmac_f32_e32 v15, v58, v17
	v_pk_fma_f32 v[10:11], v[58:59], v[24:25], v[10:11] op_sel_hi:[0,1,1]
	v_pk_fma_f32 v[8:9], v[58:59], v[40:41], v[8:9] op_sel_hi:[0,1,1]
	s_waitcnt vmcnt(29)
	v_fmac_f32_e32 v15, v60, v18
	v_pk_fma_f32 v[10:11], v[60:61], v[32:33], v[10:11] op_sel_hi:[0,1,1]
	v_pk_fma_f32 v[8:9], v[60:61], v[48:49], v[8:9] op_sel_hi:[0,1,1]
	s_waitcnt vmcnt(28)
	v_fmac_f32_e32 v15, v62, v19
	v_pk_fma_f32 v[10:11], v[62:63], v[26:27], v[10:11] op_sel_hi:[0,1,1]
	v_pk_fma_f32 v[8:9], v[62:63], v[42:43], v[8:9] op_sel_hi:[0,1,1]
	s_waitcnt vmcnt(27)
	v_fmac_f32_e32 v15, v64, v20
	v_pk_fma_f32 v[10:11], v[64:65], v[34:35], v[10:11] op_sel_hi:[0,1,1]
	v_pk_fma_f32 v[8:9], v[64:65], v[50:51], v[8:9] op_sel_hi:[0,1,1]
	s_waitcnt vmcnt(26)
	v_fmac_f32_e32 v15, v66, v21
	v_pk_fma_f32 v[10:11], v[66:67], v[28:29], v[10:11] op_sel_hi:[0,1,1]
	v_pk_fma_f32 v[8:9], v[66:67], v[44:45], v[8:9] op_sel_hi:[0,1,1]
	s_waitcnt vmcnt(25)
	v_fmac_f32_e32 v15, v68, v22
	v_pk_fma_f32 v[10:11], v[68:69], v[36:37], v[10:11] op_sel_hi:[0,1,1]
	v_pk_fma_f32 v[8:9], v[68:69], v[52:53], v[8:9] op_sel_hi:[0,1,1]
	s_waitcnt vmcnt(24)
	v_fmac_f32_e32 v15, v70, v23
	v_pk_fma_f32 v[10:11], v[70:71], v[30:31], v[10:11] op_sel_hi:[0,1,1]
	v_pk_fma_f32 v[8:9], v[70:71], v[46:47], v[8:9] op_sel_hi:[0,1,1]
	ds_read_b128 v[16:19], v14
	ds_read_b128 v[20:23], v14 offset:16
	ds_read_b128 v[24:27], v14 offset:4096
	ds_read_b128 v[28:31], v14 offset:4112
	ds_read_b128 v[32:35], v14 offset:8192
	ds_read_b128 v[36:39], v14 offset:8208
	ds_read_b128 v[40:43], v14 offset:12288
	ds_read_b128 v[44:47], v14 offset:12304
	ds_read_b128 v[48:51], v14 offset:16384
	ds_read_b128 v[52:55], v14 offset:16400
	s_waitcnt lgkmcnt(5)
	v_mov_b32_e32 v72, v32
	v_mov_b32_e32 v73, v24
	s_waitcnt lgkmcnt(3)
	v_mov_b32_e32 v75, v40
	s_waitcnt lgkmcnt(1)
	v_mov_b32_e32 v74, v48
	v_mov_b32_e32 v24, v33
	v_mov_b32_e32 v40, v49
	v_mov_b32_e32 v32, v34
	v_mov_b32_e32 v33, v26
	v_mov_b32_e32 v48, v50
	v_mov_b32_e32 v49, v42
	v_mov_b32_e32 v26, v35
	v_mov_b32_e32 v42, v51
	v_mov_b32_e32 v34, v36
	v_mov_b32_e32 v35, v28
	s_waitcnt lgkmcnt(0)
	v_mov_b32_e32 v50, v52
	v_mov_b32_e32 v51, v44
	v_mov_b32_e32 v28, v37
	v_mov_b32_e32 v44, v53
	v_mov_b32_e32 v36, v38
	v_mov_b32_e32 v37, v30
	v_mov_b32_e32 v52, v54
	v_mov_b32_e32 v53, v46
	v_mov_b32_e32 v30, v39
	v_mov_b32_e32 v46, v55
	v_add_u32_e32 v14, 32, v14
	s_waitcnt vmcnt(23)
	v_fmac_f32_e32 v15, v76, v16
	v_pk_fma_f32 v[10:11], v[76:77], v[72:73], v[10:11] op_sel_hi:[0,1,1]
	v_pk_fma_f32 v[8:9], v[76:77], v[74:75], v[8:9] op_sel_hi:[0,1,1]
	s_waitcnt vmcnt(22)
	v_fmac_f32_e32 v15, v78, v17
	v_pk_fma_f32 v[10:11], v[78:79], v[24:25], v[10:11] op_sel_hi:[0,1,1]
	v_pk_fma_f32 v[8:9], v[78:79], v[40:41], v[8:9] op_sel_hi:[0,1,1]
	s_waitcnt vmcnt(21)
	v_fmac_f32_e32 v15, v80, v18
	v_pk_fma_f32 v[10:11], v[80:81], v[32:33], v[10:11] op_sel_hi:[0,1,1]
	v_pk_fma_f32 v[8:9], v[80:81], v[48:49], v[8:9] op_sel_hi:[0,1,1]
	s_waitcnt vmcnt(20)
	v_fmac_f32_e32 v15, v82, v19
	v_pk_fma_f32 v[10:11], v[82:83], v[26:27], v[10:11] op_sel_hi:[0,1,1]
	v_pk_fma_f32 v[8:9], v[82:83], v[42:43], v[8:9] op_sel_hi:[0,1,1]
	s_waitcnt vmcnt(19)
	v_fmac_f32_e32 v15, v84, v20
	v_pk_fma_f32 v[10:11], v[84:85], v[34:35], v[10:11] op_sel_hi:[0,1,1]
	v_pk_fma_f32 v[8:9], v[84:85], v[50:51], v[8:9] op_sel_hi:[0,1,1]
	s_waitcnt vmcnt(18)
	v_fmac_f32_e32 v15, v86, v21
	v_pk_fma_f32 v[10:11], v[86:87], v[28:29], v[10:11] op_sel_hi:[0,1,1]
	v_pk_fma_f32 v[8:9], v[86:87], v[44:45], v[8:9] op_sel_hi:[0,1,1]
	s_waitcnt vmcnt(17)
	v_fmac_f32_e32 v15, v88, v22
	v_pk_fma_f32 v[10:11], v[88:89], v[36:37], v[10:11] op_sel_hi:[0,1,1]
	v_pk_fma_f32 v[8:9], v[88:89], v[52:53], v[8:9] op_sel_hi:[0,1,1]
	s_waitcnt vmcnt(16)
	v_fmac_f32_e32 v15, v90, v23
	v_pk_fma_f32 v[10:11], v[90:91], v[30:31], v[10:11] op_sel_hi:[0,1,1]
	v_pk_fma_f32 v[8:9], v[90:91], v[46:47], v[8:9] op_sel_hi:[0,1,1]
	ds_read_b128 v[16:19], v14
	ds_read_b128 v[20:23], v14 offset:16
	ds_read_b128 v[24:27], v14 offset:4096
	ds_read_b128 v[28:31], v14 offset:4112
	ds_read_b128 v[32:35], v14 offset:8192
	ds_read_b128 v[36:39], v14 offset:8208
	ds_read_b128 v[40:43], v14 offset:12288
	ds_read_b128 v[44:47], v14 offset:12304
	ds_read_b128 v[48:51], v14 offset:16384
	ds_read_b128 v[52:55], v14 offset:16400
	s_waitcnt lgkmcnt(5)
	v_mov_b32_e32 v72, v32
	v_mov_b32_e32 v73, v24
	s_waitcnt lgkmcnt(3)
	v_mov_b32_e32 v75, v40
	s_waitcnt lgkmcnt(1)
	v_mov_b32_e32 v74, v48
	v_mov_b32_e32 v24, v33
	v_mov_b32_e32 v40, v49
	v_mov_b32_e32 v32, v34
	v_mov_b32_e32 v33, v26
	v_mov_b32_e32 v48, v50
	v_mov_b32_e32 v49, v42
	v_mov_b32_e32 v26, v35
	v_mov_b32_e32 v42, v51
	v_mov_b32_e32 v34, v36
	v_mov_b32_e32 v35, v28
	s_waitcnt lgkmcnt(0)
	v_mov_b32_e32 v50, v52
	v_mov_b32_e32 v51, v44
	v_mov_b32_e32 v28, v37
	v_mov_b32_e32 v44, v53
	v_mov_b32_e32 v36, v38
	v_mov_b32_e32 v37, v30
	v_mov_b32_e32 v52, v54
	v_mov_b32_e32 v53, v46
	v_mov_b32_e32 v30, v39
	v_mov_b32_e32 v46, v55
	v_add_u32_e32 v14, 32, v14
	s_waitcnt vmcnt(15)
	v_fmac_f32_e32 v15, v92, v16
	v_pk_fma_f32 v[10:11], v[92:93], v[72:73], v[10:11] op_sel_hi:[0,1,1]
	v_pk_fma_f32 v[8:9], v[92:93], v[74:75], v[8:9] op_sel_hi:[0,1,1]
	s_waitcnt vmcnt(14)
	v_fmac_f32_e32 v15, v94, v17
	v_pk_fma_f32 v[10:11], v[94:95], v[24:25], v[10:11] op_sel_hi:[0,1,1]
	v_pk_fma_f32 v[8:9], v[94:95], v[40:41], v[8:9] op_sel_hi:[0,1,1]
	s_waitcnt vmcnt(13)
	v_fmac_f32_e32 v15, v96, v18
	v_pk_fma_f32 v[10:11], v[96:97], v[32:33], v[10:11] op_sel_hi:[0,1,1]
	v_pk_fma_f32 v[8:9], v[96:97], v[48:49], v[8:9] op_sel_hi:[0,1,1]
	s_waitcnt vmcnt(12)
	v_fmac_f32_e32 v15, v98, v19
	v_pk_fma_f32 v[10:11], v[98:99], v[26:27], v[10:11] op_sel_hi:[0,1,1]
	v_pk_fma_f32 v[8:9], v[98:99], v[42:43], v[8:9] op_sel_hi:[0,1,1]
	s_waitcnt vmcnt(11)
	v_fmac_f32_e32 v15, v100, v20
	v_pk_fma_f32 v[10:11], v[100:101], v[34:35], v[10:11] op_sel_hi:[0,1,1]
	v_pk_fma_f32 v[8:9], v[100:101], v[50:51], v[8:9] op_sel_hi:[0,1,1]
	s_waitcnt vmcnt(10)
	v_fmac_f32_e32 v15, v102, v21
	v_pk_fma_f32 v[10:11], v[102:103], v[28:29], v[10:11] op_sel_hi:[0,1,1]
	v_pk_fma_f32 v[8:9], v[102:103], v[44:45], v[8:9] op_sel_hi:[0,1,1]
	s_waitcnt vmcnt(9)
	v_fmac_f32_e32 v15, v104, v22
	v_pk_fma_f32 v[10:11], v[104:105], v[36:37], v[10:11] op_sel_hi:[0,1,1]
	v_pk_fma_f32 v[8:9], v[104:105], v[52:53], v[8:9] op_sel_hi:[0,1,1]
	s_waitcnt vmcnt(8)
	v_fmac_f32_e32 v15, v106, v23
	v_pk_fma_f32 v[10:11], v[106:107], v[30:31], v[10:11] op_sel_hi:[0,1,1]
	v_pk_fma_f32 v[8:9], v[106:107], v[46:47], v[8:9] op_sel_hi:[0,1,1]
	ds_read_b128 v[16:19], v14
	ds_read_b128 v[20:23], v14 offset:16
	ds_read_b128 v[24:27], v14 offset:4096
	ds_read_b128 v[28:31], v14 offset:4112
	ds_read_b128 v[32:35], v14 offset:8192
	ds_read_b128 v[36:39], v14 offset:8208
	ds_read_b128 v[40:43], v14 offset:12288
	ds_read_b128 v[44:47], v14 offset:12304
	ds_read_b128 v[48:51], v14 offset:16384
	ds_read_b128 v[52:55], v14 offset:16400
	s_waitcnt lgkmcnt(5)
	v_mov_b32_e32 v72, v32
	v_mov_b32_e32 v73, v24
	s_waitcnt lgkmcnt(3)
	v_mov_b32_e32 v75, v40
	s_waitcnt lgkmcnt(1)
	v_mov_b32_e32 v74, v48
	v_mov_b32_e32 v24, v33
	v_mov_b32_e32 v40, v49
	v_mov_b32_e32 v32, v34
	v_mov_b32_e32 v33, v26
	v_mov_b32_e32 v48, v50
	v_mov_b32_e32 v49, v42
	v_mov_b32_e32 v26, v35
	v_mov_b32_e32 v42, v51
	v_mov_b32_e32 v34, v36
	v_mov_b32_e32 v35, v28
	s_waitcnt lgkmcnt(0)
	v_mov_b32_e32 v50, v52
	v_mov_b32_e32 v51, v44
	v_mov_b32_e32 v28, v37
	v_mov_b32_e32 v44, v53
	v_mov_b32_e32 v36, v38
	v_mov_b32_e32 v37, v30
	v_mov_b32_e32 v52, v54
	v_mov_b32_e32 v53, v46
	v_mov_b32_e32 v30, v39
	v_mov_b32_e32 v46, v55
	v_add_u32_e32 v14, 32, v14
	s_waitcnt vmcnt(7)
	v_fmac_f32_e32 v15, v108, v16
	v_pk_fma_f32 v[10:11], v[108:109], v[72:73], v[10:11] op_sel_hi:[0,1,1]
	v_pk_fma_f32 v[8:9], v[108:109], v[74:75], v[8:9] op_sel_hi:[0,1,1]
	s_waitcnt vmcnt(6)
	v_fmac_f32_e32 v15, v110, v17
	v_pk_fma_f32 v[10:11], v[110:111], v[24:25], v[10:11] op_sel_hi:[0,1,1]
	v_pk_fma_f32 v[8:9], v[110:111], v[40:41], v[8:9] op_sel_hi:[0,1,1]
	s_waitcnt vmcnt(5)
	v_fmac_f32_e32 v15, v112, v18
	v_pk_fma_f32 v[10:11], v[112:113], v[32:33], v[10:11] op_sel_hi:[0,1,1]
	v_pk_fma_f32 v[8:9], v[112:113], v[48:49], v[8:9] op_sel_hi:[0,1,1]
	s_waitcnt vmcnt(4)
	v_fmac_f32_e32 v15, v114, v19
	v_pk_fma_f32 v[10:11], v[114:115], v[26:27], v[10:11] op_sel_hi:[0,1,1]
	v_pk_fma_f32 v[8:9], v[114:115], v[42:43], v[8:9] op_sel_hi:[0,1,1]
	s_waitcnt vmcnt(3)
	v_fmac_f32_e32 v15, v116, v20
	v_pk_fma_f32 v[10:11], v[116:117], v[34:35], v[10:11] op_sel_hi:[0,1,1]
	v_pk_fma_f32 v[8:9], v[116:117], v[50:51], v[8:9] op_sel_hi:[0,1,1]
	s_waitcnt vmcnt(2)
	v_fmac_f32_e32 v15, v118, v21
	v_pk_fma_f32 v[10:11], v[118:119], v[28:29], v[10:11] op_sel_hi:[0,1,1]
	v_pk_fma_f32 v[8:9], v[118:119], v[44:45], v[8:9] op_sel_hi:[0,1,1]
	s_waitcnt vmcnt(1)
	v_fmac_f32_e32 v15, v120, v22
	v_pk_fma_f32 v[10:11], v[120:121], v[36:37], v[10:11] op_sel_hi:[0,1,1]
	v_pk_fma_f32 v[8:9], v[120:121], v[52:53], v[8:9] op_sel_hi:[0,1,1]
	s_waitcnt vmcnt(0)
	v_fmac_f32_e32 v15, v122, v23
	v_pk_fma_f32 v[10:11], v[122:123], v[30:31], v[10:11] op_sel_hi:[0,1,1]
	v_pk_fma_f32 v[8:9], v[122:123], v[46:47], v[8:9] op_sel_hi:[0,1,1]
	s_cmp_eq_u32 s6, 0x300000
	s_cbranch_scc0 .LBB0_11
	ds_write2st64_b32 v1, v15, v11 offset0:80 offset1:81
	ds_write2st64_b32 v1, v10, v9 offset0:82 offset1:83
	ds_write_b32 v1, v8 offset:21504
	s_waitcnt lgkmcnt(0)
	s_barrier
	s_and_saveexec_b64 s[0:1], vcc
	s_cbranch_execz .LBB0_9
	s_mul_i32 s6, s15, 0x1800
	s_add_i32 s6, s6, s4
	v_or_b32_e32 v6, s6, v148
	v_ashrrev_i32_e32 v7, 31, v6
	v_lshl_add_u64 v[6:7], v[6:7], 2, s[66:67]
	global_load_dword v20, v[6:7], off
	ds_read2st64_b32 v[6:7], v13 offset0:80 offset1:85
	ds_read2st64_b32 v[8:9], v13 offset0:90 offset1:95
	ds_read2st64_b32 v[10:11], v13 offset0:100 offset1:105
	ds_read2st64_b32 v[14:15], v13 offset0:110 offset1:115
	v_mad_u64_u32 v[16:17], s[6:7], s15, 5, v[158:159]
	s_waitcnt lgkmcnt(3)
	v_add_f32_e32 v6, 0, v6
	v_add_f32_e32 v6, v6, v7
	s_waitcnt lgkmcnt(2)
	v_add_f32_e32 v6, v6, v8
	v_add_f32_e32 v6, v6, v9
	s_waitcnt lgkmcnt(1)
	v_add_f32_e32 v6, v6, v10
	v_mov_b64_e32 v[18:19], s[90:91]
	v_add_f32_e32 v6, v6, v11
	v_mad_i64_i32 v[16:17], s[6:7], v16, s2, v[18:19]
	s_waitcnt lgkmcnt(0)
	v_add_f32_e32 v6, v6, v14
	v_lshl_add_u64 v[16:17], s[4:5], 2, v[16:17]
	v_add_f32_e32 v6, v6, v15
	s_waitcnt vmcnt(0)
	v_add_f32_e32 v8, v6, v20
	v_lshl_add_u64 v[6:7], v[16:17], 0, v[2:3]
	global_store_dword v[6:7], v8, off
	s_branch .LBB0_9
